# v16 + pass2: state-update reads issued under the mask/PV code, 24 v_pk_mul in prepare/norm, norm reads hoisted behind barrier 1
# speedup vs baseline: 1.0028x; 1.0028x over previous
.LBB0_1330:
	s_add_i32 s26, s26, 1
	s_mov_b64 s[20:21], 0x10000
	s_waitcnt vmcnt(4)
	v_add_f32_e32 v170, v148, v149
	v_add_f32_e32 v171, v150, v151
	v_add_f32_e32 v172, v152, v153
	v_add_f32_e32 v170, v170, v171
	v_add_f32_e32 v173, v154, v155
	v_add_f32_e32 v172, v172, v173
	v_add_f32_e32 v170, v170, v172
	v_fmamk_f32 v170, v170, 0x3c000000, v218
	v_rsq_f32_e32 v170, v170
	v_add_f32_e32 v174, v156, v157
	v_add_f32_e32 v175, v158, v159
	v_add_f32_e32 v176, v162, v163
	v_add_f32_e32 v174, v174, v175
	v_add_f32_e32 v177, v164, v165
	v_add_f32_e32 v176, v176, v177
	v_add_f32_e32 v174, v174, v176
	v_fmamk_f32 v174, v174, 0x3c000000, v218
	v_rsq_f32_e32 v174, v174
	v_lshlrev_b32_e32 v178, 16, v166
	v_and_b32_e32 v179, 0xffff0000, v166
	v_lshlrev_b32_e32 v200, 16, v167
	v_and_b32_e32 v201, 0xffff0000, v167
	v_lshlrev_b32_e32 v202, 16, v168
	v_and_b32_e32 v203, 0xffff0000, v168
	v_lshlrev_b32_e32 v204, 16, v169
	v_and_b32_e32 v205, 0xffff0000, v169
	v_pk_mul_f32 v[206:207], v[62:63], v[170:171] op_sel_hi:[1,0]
	v_pk_mul_f32 v[208:209], v[64:65], v[170:171] op_sel_hi:[1,0]
	v_pk_mul_f32 v[210:211], v[58:59], v[174:175] op_sel_hi:[1,0]
	v_pk_mul_f32 v[212:213], v[60:61], v[174:175] op_sel_hi:[1,0]
	v_pk_mul_f32 v[206:207], v[224:225], v[206:207]
	v_pk_mul_f32 v[208:209], v[226:227], v[208:209]
	v_pk_mul_f32 v[210:211], v[224:225], v[210:211]
	v_pk_mul_f32 v[212:213], v[226:227], v[212:213]
	v_pk_mul_f32 v[206:207], v[206:207], v[178:179]
	v_pk_mul_f32 v[208:209], v[208:209], v[200:201]
	v_pk_mul_f32 v[210:211], v[210:211], v[202:203]
	v_pk_mul_f32 v[212:213], v[212:213], v[204:205]
	v_cvt_pk_bf16_f32 v148, v206, v207
	v_cvt_pk_bf16_f32 v149, v208, v209
	v_cvt_pk_bf16_f32 v150, v210, v211
	v_cvt_pk_bf16_f32 v151, v212, v213
	ds_write_b64 v125, v[148:149] offset:8704
	ds_write_b64 v125, v[150:151] offset:13056
	s_cmp_lg_u32 s26, 8
	s_waitcnt lgkmcnt(0)
	s_barrier
	v_add3_u32 v58, s27, v93, v80
	ds_read_b128 v[58:61], v58 offset:8704
	s_waitcnt lgkmcnt(0)
	global_store_dwordx4 v[88:89], v[58:61], off
	v_lshl_add_u64 v[88:89], v[88:89], 0, s[20:21]
	s_mov_b64 s[20:21], 0x2c000
	v_lshl_add_u64 v[90:91], v[90:91], 0, s[20:21]
	s_cbranch_scc0 .LBB0_1325

.LBB0_1334:
	s_mul_i32 s22, s22, 0xe400
	s_add_i32 s27, s22, 0
	v_add3_u32 v147, s27, v104, v109
	s_add_i32 s29, s27, s19
	ds_read_b64 v[148:149], v147
	ds_read_b64 v[150:151], v147 offset:32
	ds_read_b64 v[152:153], v147 offset:4352
	ds_read_b64 v[154:155], v147 offset:4384
	ds_read_b64 v[196:197], v147 offset:8704
	ds_read_b64 v[198:199], v147 offset:8736
	ds_read_b64 v[200:201], v147 offset:13056
	ds_read_b64 v[202:203], v147 offset:13088
	v_cvt_pk_bf16_f32 v126, v26, v27
	v_cvt_pk_bf16_f32 v127, v28, v29
	v_cvt_pk_bf16_f32 v128, v30, v31
	v_cvt_pk_bf16_f32 v129, v32, v33
	ds_read_b64 v[156:157], v147 offset:64
	ds_read_b64 v[158:159], v147 offset:96
	ds_read_b64 v[160:161], v147 offset:4416
	ds_read_b64 v[162:163], v147 offset:4448
	ds_read_b64 v[204:205], v147 offset:8768
	ds_read_b64 v[206:207], v147 offset:8800
	ds_read_b64 v[208:209], v147 offset:13120
	ds_read_b64 v[210:211], v147 offset:13152
	v_cvt_pk_bf16_f32 v130, v34, v35
	v_cvt_pk_bf16_f32 v131, v36, v37
	v_cvt_pk_bf16_f32 v132, v38, v39
	v_cvt_pk_bf16_f32 v133, v40, v41
	s_waitcnt lgkmcnt(8)
	v_mfma_f32_16x16x32_bf16 v[62:65], v[126:129], v[148:151], 0
	v_mfma_f32_16x16x32_bf16 v[58:61], v[126:129], v[152:155], 0
	v_mfma_f32_16x16x32_bf16 v[164:167], v[196:199], v[148:151], 0
	v_mfma_f32_16x16x32_bf16 v[168:171], v[196:199], v[152:155], 0
	v_mfma_f32_16x16x32_bf16 v[172:175], v[200:203], v[152:155], 0
	ds_read_b64 v[148:149], v147 offset:128
	ds_read_b64 v[150:151], v147 offset:160
	ds_read_b64 v[152:153], v147 offset:4480
	ds_read_b64 v[154:155], v147 offset:4512
	ds_read_b64 v[196:197], v147 offset:8832
	ds_read_b64 v[198:199], v147 offset:8864
	ds_read_b64 v[200:201], v147 offset:13184
	ds_read_b64 v[202:203], v147 offset:13216
	v_cvt_pk_bf16_f32 v134, v42, v43
	v_cvt_pk_bf16_f32 v135, v44, v45
	v_cvt_pk_bf16_f32 v136, v46, v47
	v_cvt_pk_bf16_f32 v137, v48, v49
	s_waitcnt lgkmcnt(8)
	v_mfma_f32_16x16x32_bf16 v[62:65], v[130:133], v[156:159], v[62:65]
	v_mfma_f32_16x16x32_bf16 v[58:61], v[130:133], v[160:163], v[58:61]
	v_mfma_f32_16x16x32_bf16 v[164:167], v[204:207], v[156:159], v[164:167]
	v_mfma_f32_16x16x32_bf16 v[168:171], v[204:207], v[160:163], v[168:171]
	v_mfma_f32_16x16x32_bf16 v[172:175], v[208:211], v[160:163], v[172:175]
	ds_read_b64 v[156:157], v147 offset:192
	ds_read_b64 v[158:159], v147 offset:224
	ds_read_b64 v[160:161], v147 offset:4544
	ds_read_b64 v[162:163], v147 offset:4576
	ds_read_b64 v[204:205], v147 offset:8896
	ds_read_b64 v[206:207], v147 offset:8928
	ds_read_b64 v[208:209], v147 offset:13248
	ds_read_b64 v[210:211], v147 offset:13280
	v_cvt_pk_bf16_f32 v138, v50, v51
	v_cvt_pk_bf16_f32 v139, v52, v53
	v_cvt_pk_bf16_f32 v140, v54, v55
	v_cvt_pk_bf16_f32 v141, v56, v57
	s_waitcnt lgkmcnt(8)
	v_mfma_f32_16x16x32_bf16 v[62:65], v[134:137], v[148:151], v[62:65]
	v_mfma_f32_16x16x32_bf16 v[58:61], v[134:137], v[152:155], v[58:61]
	v_mfma_f32_16x16x32_bf16 v[164:167], v[196:199], v[148:151], v[164:167]
	v_mfma_f32_16x16x32_bf16 v[168:171], v[196:199], v[152:155], v[168:171]
	v_mfma_f32_16x16x32_bf16 v[172:175], v[200:203], v[152:155], v[172:175]
	v_add_u32_e32 v176, s27, v106
	v_add_u32_e32 v68, v176, v123
	ds_read_b64_tr_b16 v[66:67], v68 offset:37888
	ds_read_b64_tr_b16 v[68:69], v68 offset:43008
	s_waitcnt lgkmcnt(2)
	v_mfma_f32_16x16x32_bf16 v[62:65], v[138:141], v[156:159], v[62:65]
	v_mfma_f32_16x16x32_bf16 v[58:61], v[138:141], v[160:163], v[58:61]
	v_mfma_f32_16x16x32_bf16 v[164:167], v[204:207], v[156:159], v[164:167]
	v_mfma_f32_16x16x32_bf16 v[168:171], v[204:207], v[160:163], v[168:171]
	v_mfma_f32_16x16x32_bf16 v[172:175], v[208:211], v[160:163], v[172:175]
	v_add_u32_e32 v125, s27, v105
	v_add_u32_e32 v134, v176, v110
	ds_read_b128 v[196:199], v125 offset:56832
	ds_read_b64_tr_b16 v[148:149], v134 offset:27648
	ds_read_b64_tr_b16 v[150:151], v134 offset:32768
	ds_read_b128 v[200:203], v125 offset:56896
	ds_read_b64_tr_b16 v[152:153], v134 offset:27680
	ds_read_b64_tr_b16 v[154:155], v134 offset:32800
	v_mov_b32_e32 v177, s55
	v_mov_b32_e32 v72, v16
	v_mov_b32_e32 v73, v16
	s_nop 0
	v_cndmask_b32_e64 v165, 0, v165, s[6:7]
	v_cndmask_b32_e64 v166, v166, 0, s[8:9]
	v_cndmask_b32_e64 v167, v167, 0, s[10:11]
	v_cndmask_b32_e64 v164, v164, v177, s[4:5]
	v_cvt_pk_bf16_f32 v70, v164, v165
	v_cvt_pk_bf16_f32 v71, v166, v167
	v_cndmask_b32_e64 v172, v172, v177, s[4:5]
	v_cndmask_b32_e64 v173, v173, 0, s[12:13]
	v_cndmask_b32_e64 v174, v174, 0, s[14:15]
	v_cndmask_b32_e64 v175, v175, 0, s[16:17]
	s_waitcnt lgkmcnt(6)
	v_mfma_f32_16x16x32_bf16 v[62:65], v[66:69], v[70:73], v[62:65]
	v_cvt_pk_bf16_f32 v70, v168, v169
	v_cvt_pk_bf16_f32 v71, v170, v171
	v_cvt_pk_bf16_f32 v72, v172, v173
	v_cvt_pk_bf16_f32 v73, v174, v175
	s_nop 1
	v_mfma_f32_16x16x32_bf16 v[58:61], v[66:69], v[70:73], v[58:61]
	s_waitcnt lgkmcnt(3)
	v_pk_mul_f32 v[26:27], v[26:27], v[196:197]
	v_pk_mul_f32 v[28:29], v[28:29], v[198:199]
	ds_read_b128 v[204:207], v125 offset:56960
	ds_read_b64_tr_b16 v[156:157], v134 offset:27712
	ds_read_b64_tr_b16 v[158:159], v134 offset:32832
	v_mfma_f32_16x16x32_bf16 v[26:29], v[148:151], v[66:69], v[26:29]
	s_waitcnt lgkmcnt(3)
	v_pk_mul_f32 v[30:31], v[30:31], v[200:201]
	v_pk_mul_f32 v[32:33], v[32:33], v[202:203]
	ds_read_b128 v[196:199], v125 offset:57024
	ds_read_b64_tr_b16 v[148:149], v134 offset:27744
	ds_read_b64_tr_b16 v[150:151], v134 offset:32864
	v_mfma_f32_16x16x32_bf16 v[30:33], v[152:155], v[66:69], v[30:33]
	s_waitcnt lgkmcnt(3)
	v_pk_mul_f32 v[34:35], v[34:35], v[204:205]
	v_pk_mul_f32 v[36:37], v[36:37], v[206:207]
	ds_read_b128 v[200:203], v125 offset:57088
	ds_read_b64_tr_b16 v[152:153], v134 offset:27776
	ds_read_b64_tr_b16 v[154:155], v134 offset:32896
	v_mfma_f32_16x16x32_bf16 v[34:37], v[156:159], v[66:69], v[34:37]
	s_waitcnt lgkmcnt(3)
	v_pk_mul_f32 v[38:39], v[38:39], v[196:197]
	v_pk_mul_f32 v[40:41], v[40:41], v[198:199]
	ds_read_b128 v[204:207], v125 offset:57152
	ds_read_b64_tr_b16 v[156:157], v134 offset:27808
	ds_read_b64_tr_b16 v[158:159], v134 offset:32928
	v_mfma_f32_16x16x32_bf16 v[38:41], v[148:151], v[66:69], v[38:41]
	s_waitcnt lgkmcnt(3)
	v_pk_mul_f32 v[42:43], v[42:43], v[200:201]
	v_pk_mul_f32 v[44:45], v[44:45], v[202:203]
	ds_read_b128 v[196:199], v125 offset:57216
	ds_read_b64_tr_b16 v[148:149], v134 offset:27840
	ds_read_b64_tr_b16 v[150:151], v134 offset:32960
	v_mfma_f32_16x16x32_bf16 v[42:45], v[152:155], v[66:69], v[42:45]
	s_waitcnt lgkmcnt(3)
	v_pk_mul_f32 v[46:47], v[46:47], v[204:205]
	v_pk_mul_f32 v[48:49], v[48:49], v[206:207]
	ds_read_b128 v[200:203], v125 offset:57280
	ds_read_b64_tr_b16 v[152:153], v134 offset:27872
	ds_read_b64_tr_b16 v[154:155], v134 offset:32992
	v_mfma_f32_16x16x32_bf16 v[46:49], v[156:159], v[66:69], v[46:49]
	s_waitcnt lgkmcnt(3)
	v_pk_mul_f32 v[50:51], v[50:51], v[196:197]
	v_pk_mul_f32 v[52:53], v[52:53], v[198:199]
	s_nop 1
	v_mfma_f32_16x16x32_bf16 v[50:53], v[148:151], v[66:69], v[50:53]
	s_waitcnt lgkmcnt(0)
	v_pk_mul_f32 v[54:55], v[54:55], v[200:201]
	v_pk_mul_f32 v[56:57], v[56:57], v[202:203]
	s_nop 1
	v_mfma_f32_16x16x32_bf16 v[54:57], v[152:155], v[66:69], v[54:57]
	v_mul_f32_e32 v148, v62, v62
	v_mul_f32_e32 v149, v58, v58
	v_fmac_f32_e32 v148, v63, v63
	v_fmac_f32_e32 v149, v59, v59
	v_fmac_f32_e32 v148, v64, v64
	v_fmac_f32_e32 v149, v60, v60
	v_fmac_f32_e32 v148, v65, v65
	v_fmac_f32_e32 v149, v61, v61
	v_lshl_add_u32 v156, v77, 5, s29
	s_nop 0
	v_permlane16_swap_b32_e32 v148, v149
	v_add_f32_e32 v148, v148, v149
	v_mov_b32_e32 v149, v148
	s_nop 1
	v_permlane32_swap_b32_e32 v148, v149
	v_add_f32_e32 v148, v148, v149
	s_mov_b64 s[22:23], exec
	s_mov_b32 exec_hi, 0
	ds_write_b32 v156, v148 offset:57344
	s_mov_b64 exec, s[22:23]
	s_waitcnt lgkmcnt(0)
	s_barrier
	v_lshl_add_u32 v160, v95, 5, s27
	ds_read_b128 v[148:151], v160 offset:57344
	ds_read_b128 v[152:155], v160 offset:57360
	ds_read_b128 v[156:159], v160 offset:57856
	ds_read_b128 v[162:165], v160 offset:57872
	v_add3_u32 v125, s27, v109, v222
	ds_read_b64 v[166:167], v125 offset:48128
	ds_read_b64 v[168:169], v125 offset:52480
	s_andn2_b64 vcc, exec, s[20:21]
	s_cbranch_vccnz .Lp2_Fwait
	v_add3_u32 v68, s28, v96, v120
	ds_read_b64_tr_b16 v[66:67], v68 offset:17408
	ds_read_b64_tr_b16 v[68:69], v68 offset:18688
	v_add_u32_e32 v138, s28, v236
	v_add3_u32 v139, s28, v109, v222
	ds_read_b64 v[180:181], v138 offset:17408
	ds_read_b64 v[182:183], v138 offset:22528
	ds_read_b64 v[184:185], v139
	ds_read_b64 v[186:187], v139 offset:4352
	s_waitcnt lgkmcnt(4)
	v_mfma_f32_16x16x32_bf16 v[70:73], v[66:69], v[4:7], 0
	v_mfma_f32_16x16x32_bf16 v[66:69], v[66:69], v[0:3], 0
	s_mov_b32 s23, 0x42e60000
	s_waitcnt lgkmcnt(0)
	v_lshlrev_b32_e32 v188, 16, v180
	v_and_b32_e32 v189, 0xffff0000, v180
	v_lshlrev_b32_e32 v190, 16, v181
	v_and_b32_e32 v191, 0xffff0000, v181
	v_lshlrev_b32_e32 v192, 16, v182
	v_and_b32_e32 v193, 0xffff0000, v182
	v_lshlrev_b32_e32 v194, 16, v183
	v_and_b32_e32 v195, 0xffff0000, v183
	v_lshlrev_b32_e32 v196, 16, v184
	v_and_b32_e32 v197, 0xffff0000, v184
	v_lshlrev_b32_e32 v198, 16, v185
	v_and_b32_e32 v199, 0xffff0000, v185
	v_lshlrev_b32_e32 v200, 16, v186
	v_and_b32_e32 v201, 0xffff0000, v186
	v_lshlrev_b32_e32 v202, 16, v187
	v_and_b32_e32 v203, 0xffff0000, v187
	v_exp_f32_e32 v188, v188
	v_exp_f32_e32 v189, v189
	v_exp_f32_e32 v190, v190
	v_exp_f32_e32 v191, v191
	v_exp_f32_e32 v192, v192
	v_exp_f32_e32 v193, v193
	v_exp_f32_e32 v194, v194
	v_exp_f32_e32 v195, v195
	v_sub_f32_e32 v188, 1.0, v188
	v_sub_f32_e32 v189, 1.0, v189
	v_sub_f32_e32 v190, 1.0, v190
	v_sub_f32_e32 v191, 1.0, v191
	v_sub_f32_e32 v192, 1.0, v192
	v_sub_f32_e32 v193, 1.0, v193
	v_sub_f32_e32 v194, 1.0, v194
	v_sub_f32_e32 v195, 1.0, v195
	v_exp_f32_e32 v204, v70
	v_exp_f32_e32 v205, v71
	v_exp_f32_e32 v206, v72
	v_exp_f32_e32 v207, v73
	v_exp_f32_e32 v208, v66
	v_exp_f32_e32 v209, v67
	v_exp_f32_e32 v210, v68
	v_exp_f32_e32 v211, v69
	v_sub_f32_dpp v126, v66, v70 row_newbcast:15 row_mask:0xf bank_mask:0xf
	v_sub_f32_dpp v127, v67, v71 row_newbcast:15 row_mask:0xf bank_mask:0xf
	v_sub_f32_dpp v128, v68, v72 row_newbcast:15 row_mask:0xf bank_mask:0xf
	v_sub_f32_dpp v129, v69, v73 row_newbcast:15 row_mask:0xf bank_mask:0xf
	v_sub_f32_dpp v130, v66, v66 row_newbcast:15 row_mask:0xf bank_mask:0xf
	v_sub_f32_dpp v131, v67, v67 row_newbcast:15 row_mask:0xf bank_mask:0xf
	v_sub_f32_dpp v132, v68, v68 row_newbcast:15 row_mask:0xf bank_mask:0xf
	v_sub_f32_dpp v133, v69, v69 row_newbcast:15 row_mask:0xf bank_mask:0xf
	v_pk_mul_f32 v[196:197], v[196:197], v[204:205]
	v_pk_mul_f32 v[198:199], v[198:199], v[206:207]
	v_pk_mul_f32 v[200:201], v[200:201], v[208:209]
	v_pk_mul_f32 v[202:203], v[202:203], v[210:211]
	v_min_f32_e64 v204, -v70, s23
	v_min_f32_e64 v205, -v71, s23
	v_min_f32_e64 v206, -v72, s23
	v_min_f32_e64 v207, -v73, s23
	v_min_f32_e64 v208, -v66, s23
	v_min_f32_e64 v209, -v67, s23
	v_min_f32_e64 v210, -v68, s23
	v_min_f32_e64 v211, -v69, s23
	v_exp_f32_e32 v126, v126
	v_exp_f32_e32 v127, v127
	v_exp_f32_e32 v128, v128
	v_exp_f32_e32 v129, v129
	v_exp_f32_e32 v130, v130
	v_exp_f32_e32 v131, v131
	v_exp_f32_e32 v132, v132
	v_exp_f32_e32 v133, v133
	v_exp_f32_e32 v204, v204
	v_exp_f32_e32 v205, v205
	v_exp_f32_e32 v206, v206
	v_exp_f32_e32 v207, v207
	v_exp_f32_e32 v208, v208
	v_exp_f32_e32 v209, v209
	v_exp_f32_e32 v210, v210
	v_exp_f32_e32 v211, v211
	v_exp_f32_e32 v212, v66
	v_exp_f32_e32 v213, v67
	v_exp_f32_e32 v214, v68
	v_exp_f32_e32 v215, v69
	v_pk_mul_f32 v[126:127], v[126:127], v[188:189]
	v_pk_mul_f32 v[128:129], v[128:129], v[190:191]
	v_pk_mul_f32 v[130:131], v[130:131], v[192:193]
	v_pk_mul_f32 v[132:133], v[132:133], v[194:195]
	v_pk_mul_f32 v[204:205], v[204:205], v[188:189]
	v_pk_mul_f32 v[206:207], v[206:207], v[190:191]
	v_pk_mul_f32 v[208:209], v[208:209], v[192:193]
	v_pk_mul_f32 v[210:211], v[210:211], v[194:195]
	v_lshl_add_u32 v216, v222, 1, s28
	v_cvt_pk_bf16_f32 v180, v196, v197
	v_cvt_pk_bf16_f32 v181, v198, v199
	v_cvt_pk_bf16_f32 v182, v200, v201
	v_cvt_pk_bf16_f32 v183, v202, v203
	v_cvt_pk_bf16_f32 v184, v204, v205
	v_cvt_pk_bf16_f32 v185, v206, v207
	v_cvt_pk_bf16_f32 v186, v208, v209
	v_cvt_pk_bf16_f32 v187, v210, v211
	v_cvt_pk_bf16_f32 v134, v126, v127
	v_cvt_pk_bf16_f32 v135, v128, v129
	v_cvt_pk_bf16_f32 v136, v130, v131
	v_cvt_pk_bf16_f32 v137, v132, v133
	ds_write_b64 v139, v[180:181]
	ds_write_b64 v139, v[182:183] offset:4352
	ds_write_b64 v139, v[184:185] offset:8704
	ds_write_b64 v139, v[186:187] offset:13056
	ds_write_b64 v138, v[134:135] offset:27648
	ds_write_b64 v138, v[136:137] offset:32768
	s_and_saveexec_b64 s[20:21], s[2:3]
	ds_write_b128 v216, v[212:215] offset:56832
	s_branch .LBB0_1329
